# adds sample conv unit P-row loads hoisted into one burst (16 loads, fresh registers)
# baseline (speedup 1.0000x reference)
.LBB0_639:
	v_readlane_b32 s0, v239, 41
	v_readlane_b32 s2, v239, 42
	v_mov_b32_e32 v122, v0
	v_mov_b32_e32 v2, s0
	ds_read2_b64 v[2:5], v2 offset1:1
	s_mov_b32 s83, 0x15000
	s_mov_b32 s90, 0x17000
	s_mov_b32 s48, 0x18000
	s_mov_b32 s52, 0x19000
	s_waitcnt lgkmcnt(0)
	v_readfirstlane_b32 s0, v2
	v_mov_b32_e32 v2, s2
	v_readfirstlane_b32 s1, v3
	v_readfirstlane_b32 s35, v5
	v_readfirstlane_b32 s46, v4
	ds_read2_b64 v[2:5], v2 offset1:1
	v_readlane_b32 s2, v239, 43
	s_add_u32 s0, s0, s21
	s_addc_u32 s1, s1, s20
	s_ashr_i32 s18, s28, 31
	s_waitcnt lgkmcnt(0)
	v_readfirstlane_b32 s34, v2
	v_mov_b32_e32 v2, s2
	v_readfirstlane_b32 s19, v3
	ds_read_b64 v[2:3], v2
	s_movk_i32 s2, 0x5000
	v_lshlrev_b32_e32 v32, 1, v122
	v_ashrrev_i32_e32 v33, 31, v32
	s_waitcnt lgkmcnt(0)
	v_readfirstlane_b32 s15, v3
	v_readfirstlane_b32 s14, v2
	v_lshlrev_b64 v[2:3], 2, v[32:33]
	v_lshl_add_u64 v[56:57], s[0:1], 0, v[2:3]
	v_lshl_add_u64 v[6:7], s[14:15], 0, v[2:3]
	v_lshl_add_u64 v[34:35], v[6:7], 0, s[10:11]
	v_add_co_u32_e32 v6, vcc, s3, v34
	s_lshl_b64 s[0:1], s[38:39], 2
	s_nop 0
	v_addc_co_u32_e32 v7, vcc, 0, v35, vcc
	s_waitcnt vmcnt(0)
	flat_load_dwordx2 v[58:59], v[6:7]
	flat_load_dwordx2 v[60:61], v[56:57]
	v_add_co_u32_e32 v6, vcc, s17, v56
	s_add_u32 s46, s46, s0
	s_nop 0
	v_addc_co_u32_e32 v7, vcc, 0, v57, vcc
	flat_load_dwordx2 v[62:63], v[6:7]
	v_add_co_u32_e32 v6, vcc, s5, v56
	s_addc_u32 s47, s35, s1
	s_nop 0
	v_addc_co_u32_e32 v7, vcc, 0, v57, vcc
	flat_load_dwordx2 v[64:65], v[6:7]
	v_add_co_u32_e32 v6, vcc, s87, v56
	v_readfirstlane_b32 s23, v5
	s_nop 0
	v_addc_co_u32_e32 v7, vcc, 0, v57, vcc
	flat_load_dwordx2 v[66:67], v[6:7]
	v_add_co_u32_e32 v6, vcc, s6, v56
	v_readfirstlane_b32 s22, v4
	s_nop 0
	v_addc_co_u32_e32 v7, vcc, 0, v57, vcc
	flat_load_dwordx2 v[68:69], v[6:7]
	v_add_co_u32_e32 v6, vcc, s2, v56
	v_lshl_add_u64 v[4:5], s[46:47], 0, v[2:3]
	s_nop 0
	v_addc_co_u32_e32 v7, vcc, 0, v57, vcc
	flat_load_dwordx2 v[70:71], v[6:7]
	v_add_co_u32_e32 v6, vcc, s7, v56
	s_mov_b32 s49, 0x1a000
	s_nop 0
	v_addc_co_u32_e32 v7, vcc, 0, v57, vcc
	flat_load_dwordx2 v[72:73], v[6:7]
	v_add_co_u32_e32 v6, vcc, s16, v56
	s_mov_b32 s88, 0x1b000
	s_nop 0
	v_addc_co_u32_e32 v7, vcc, 0, v57, vcc
	flat_load_dwordx2 v[74:75], v[6:7]
	v_add_co_u32_e32 v6, vcc, s3, v56
	s_mov_b32 s3, 0x16000
	s_nop 0
	v_addc_co_u32_e32 v7, vcc, 0, v57, vcc
	flat_load_dwordx2 v[76:77], v[6:7]
	flat_load_dwordx2 v[78:79], v[4:5]
	s_nop 0
	flat_load_dwordx2 v[4:5], v[34:35]
	v_add_co_u32_e32 v6, vcc, s17, v34
	s_mov_b32 s50, 0x1c000
	s_nop 0
	v_addc_co_u32_e32 v7, vcc, 0, v35, vcc
	flat_load_dwordx2 v[92:93], v[6:7]
	v_add_co_u32_e32 v6, vcc, s5, v34
	s_mov_b32 s89, 0x1d000
	s_nop 0
	v_addc_co_u32_e32 v7, vcc, 0, v35, vcc
	flat_load_dwordx2 v[90:91], v[6:7]
	v_add_co_u32_e32 v6, vcc, s87, v34
	s_mov_b32 s35, 0x1e000
	s_nop 0
	v_addc_co_u32_e32 v7, vcc, 0, v35, vcc
	flat_load_dwordx2 v[88:89], v[6:7]
	v_add_co_u32_e32 v6, vcc, s6, v34
	s_mov_b32 s47, 0x14000
	s_nop 0
	v_addc_co_u32_e32 v7, vcc, 0, v35, vcc
	flat_load_dwordx2 v[86:87], v[6:7]
	v_add_co_u32_e32 v6, vcc, s2, v34
	s_mov_b32 s2, 0xa000
	s_nop 0
	v_addc_co_u32_e32 v7, vcc, 0, v35, vcc
	flat_load_dwordx2 v[84:85], v[6:7]
	v_add_co_u32_e32 v6, vcc, s7, v34
	s_mov_b32 s58, 0xb000
	s_nop 0
	v_addc_co_u32_e32 v7, vcc, 0, v35, vcc
	flat_load_dwordx2 v[82:83], v[6:7]
	v_add_co_u32_e32 v6, vcc, s16, v34
	s_mov_b32 s8, 0xc000
	s_nop 0
	v_addc_co_u32_e32 v7, vcc, 0, v35, vcc
	flat_load_dwordx2 v[80:81], v[6:7]
	s_mov_b32 s59, 0xd000
	s_mov_b32 s51, 0xe000
	s_mov_b32 s60, 0xf000
	s_mov_b32 s27, 0x10000
	s_mov_b32 s61, 0x11000
	s_mov_b32 s46, 0x12000
	s_mov_b32 s82, 0x13000
	s_add_u32 s14, s76, s10
	s_mov_b32 s53, 0x9000
	s_addc_u32 s15, s77, s11
	v_lshl_add_u64 v[2:3], s[14:15], 0, v[2:3]
	s_mul_i32 s14, s28, 0x7000
	s_mul_hi_i32 s15, s28, 0x7000
	s_add_u32 s14, s92, s14
	s_addc_u32 s15, s93, s15
	v_lshl_add_u64 v[32:33], v[32:33], 1, s[14:15]
	s_mov_b32 s14, 0xe002000
	s_mov_b32 s97, 0x10000
	s_waitcnt vmcnt(0) lgkmcnt(0)
	v_pk_fma_f32 v[4:5], v[60:61], v[4:5], v[78:79]
	s_nop 0
	v_pk_fma_f32 v[4:5], v[62:63], v[92:93], v[4:5]
	v_pk_fma_f32 v[92:93], v[60:61], v[92:93], v[78:79]
	v_pk_fma_f32 v[4:5], v[64:65], v[90:91], v[4:5]
	v_pk_fma_f32 v[92:93], v[62:63], v[90:91], v[92:93]
	v_pk_fma_f32 v[90:91], v[60:61], v[90:91], v[78:79]
	v_pk_fma_f32 v[4:5], v[66:67], v[88:89], v[4:5]
	v_pk_fma_f32 v[92:93], v[64:65], v[88:89], v[92:93]
	v_pk_fma_f32 v[90:91], v[62:63], v[88:89], v[90:91]
	v_pk_fma_f32 v[88:89], v[60:61], v[88:89], v[78:79]
	v_pk_fma_f32 v[4:5], v[68:69], v[86:87], v[4:5]
	v_pk_fma_f32 v[92:93], v[66:67], v[86:87], v[92:93]
	v_pk_fma_f32 v[88:89], v[62:63], v[86:87], v[88:89]
	v_pk_fma_f32 v[90:91], v[64:65], v[86:87], v[90:91]
	v_pk_fma_f32 v[86:87], v[60:61], v[86:87], v[78:79]
	v_pk_fma_f32 v[4:5], v[70:71], v[84:85], v[4:5]
	v_pk_fma_f32 v[92:93], v[68:69], v[84:85], v[92:93]
	v_pk_fma_f32 v[88:89], v[64:65], v[84:85], v[88:89]
	v_pk_fma_f32 v[90:91], v[66:67], v[84:85], v[90:91]
	v_pk_fma_f32 v[86:87], v[62:63], v[84:85], v[86:87]
	v_pk_fma_f32 v[84:85], v[60:61], v[84:85], v[78:79]
	v_pk_fma_f32 v[4:5], v[72:73], v[82:83], v[4:5]
	v_pk_fma_f32 v[92:93], v[70:71], v[82:83], v[92:93]
	v_pk_fma_f32 v[88:89], v[66:67], v[82:83], v[88:89]
	v_pk_fma_f32 v[84:85], v[62:63], v[82:83], v[84:85]
	v_pk_fma_f32 v[90:91], v[68:69], v[82:83], v[90:91]
	v_pk_fma_f32 v[86:87], v[64:65], v[82:83], v[86:87]
	v_pk_fma_f32 v[4:5], v[74:75], v[80:81], v[4:5]
	v_pk_fma_f32 v[92:93], v[72:73], v[80:81], v[92:93]
	v_pk_fma_f32 v[96:97], v[76:77], v[58:59], v[4:5]
	v_add_co_u32_e32 v4, vcc, s83, v56
	v_pk_fma_f32 v[92:93], v[74:75], v[58:59], v[92:93]
	s_nop 0
	v_addc_co_u32_e32 v5, vcc, 0, v57, vcc
	v_add_co_u32_e32 v6, vcc, s3, v56
	flat_load_dwordx2 v[4:5], v[4:5]
	s_nop 0
	v_addc_co_u32_e32 v7, vcc, 0, v57, vcc
	v_add_co_u32_e32 v8, vcc, s90, v56
	flat_load_dwordx2 v[6:7], v[6:7]
	s_nop 0
	v_addc_co_u32_e32 v9, vcc, 0, v57, vcc
	v_add_co_u32_e32 v10, vcc, s48, v56
	flat_load_dwordx2 v[8:9], v[8:9]
	s_nop 0
	v_addc_co_u32_e32 v11, vcc, 0, v57, vcc
	v_add_co_u32_e32 v12, vcc, s52, v56
	flat_load_dwordx2 v[10:11], v[10:11]
	s_nop 0
	v_addc_co_u32_e32 v13, vcc, 0, v57, vcc
	v_add_co_u32_e32 v14, vcc, s49, v56
	flat_load_dwordx2 v[12:13], v[12:13]
	s_nop 0
	v_addc_co_u32_e32 v15, vcc, 0, v57, vcc
	v_add_co_u32_e32 v16, vcc, s88, v56
	flat_load_dwordx2 v[14:15], v[14:15]
	s_nop 0
	v_addc_co_u32_e32 v17, vcc, 0, v57, vcc
	v_add_co_u32_e32 v24, vcc, s50, v56
	flat_load_dwordx2 v[16:17], v[16:17]
	s_nop 0
	v_addc_co_u32_e32 v25, vcc, 0, v57, vcc
	v_add_co_u32_e32 v26, vcc, s89, v56
	flat_load_dwordx2 v[24:25], v[24:25]
	s_nop 0
	v_addc_co_u32_e32 v27, vcc, 0, v57, vcc
	v_add_co_u32_e32 v28, vcc, s35, v56
	s_mov_b32 s35, 0x16261000
	s_nop 0
	v_addc_co_u32_e32 v29, vcc, 0, v57, vcc
	v_add_co_u32_e32 v30, vcc, s47, v56
	flat_load_dwordx2 v[26:27], v[26:27]
	s_nop 0
	v_addc_co_u32_e32 v31, vcc, 0, v57, vcc
	v_add_co_u32_e32 v36, vcc, s2, v56
	flat_load_dwordx2 v[28:29], v[28:29]
	s_nop 0
	v_addc_co_u32_e32 v37, vcc, 0, v57, vcc
	v_add_co_u32_e32 v38, vcc, s58, v56
	flat_load_dwordx2 v[30:31], v[30:31]
	s_nop 0
	v_addc_co_u32_e32 v39, vcc, 0, v57, vcc
	v_add_co_u32_e32 v40, vcc, s8, v56
	flat_load_dwordx2 v[36:37], v[36:37]
	s_nop 0
	v_addc_co_u32_e32 v41, vcc, 0, v57, vcc
	v_add_co_u32_e32 v42, vcc, s59, v56
	flat_load_dwordx2 v[38:39], v[38:39]
	s_nop 0
	v_addc_co_u32_e32 v43, vcc, 0, v57, vcc
	v_add_co_u32_e32 v44, vcc, s51, v56
	flat_load_dwordx2 v[40:41], v[40:41]
	s_nop 0
	v_addc_co_u32_e32 v45, vcc, 0, v57, vcc
	v_add_co_u32_e32 v46, vcc, s60, v56
	flat_load_dwordx2 v[42:43], v[42:43]
	s_nop 0
	v_addc_co_u32_e32 v47, vcc, 0, v57, vcc
	v_add_co_u32_e32 v48, vcc, s27, v56
	flat_load_dwordx2 v[44:45], v[44:45]
	s_nop 0
	v_addc_co_u32_e32 v49, vcc, 0, v57, vcc
	v_add_co_u32_e32 v50, vcc, s61, v56
	flat_load_dwordx2 v[46:47], v[46:47]
	s_nop 0
	v_addc_co_u32_e32 v51, vcc, 0, v57, vcc
	v_add_co_u32_e32 v52, vcc, s46, v56
	flat_load_dwordx2 v[48:49], v[48:49]
	s_nop 0
	v_addc_co_u32_e32 v53, vcc, 0, v57, vcc
	v_add_co_u32_e32 v54, vcc, s82, v56
	flat_load_dwordx2 v[50:51], v[50:51]
	s_nop 0
	v_addc_co_u32_e32 v55, vcc, 0, v57, vcc
	v_add_co_u32_e32 v56, vcc, s53, v56
	flat_load_dwordx2 v[52:53], v[52:53]
	s_nop 0
	v_addc_co_u32_e32 v57, vcc, 0, v57, vcc
	v_add_co_u32_e32 v102, vcc, s35, v2
	flat_load_dwordx2 v[54:55], v[54:55]
	s_nop 0
	v_addc_co_u32_e32 v103, vcc, 0, v3, vcc
	v_add_co_u32_e32 v94, vcc, s53, v34
	flat_load_dwordx2 v[56:57], v[56:57]
	s_nop 0
	v_addc_co_u32_e32 v95, vcc, 0, v35, vcc
	global_store_dwordx2 v[102:103], v[58:59], off offset:-4096
	v_add_co_u32_e32 v204, vcc, 0x9000, v34
	s_nop 1
	v_addc_co_u32_e32 v205, vcc, 0, v35, vcc
	global_load_dwordx2 v[146:147], v[204:205], off
	v_add_co_u32_e32 v204, vcc, 0xa000, v34
	s_nop 1
	v_addc_co_u32_e32 v205, vcc, 0, v35, vcc
	global_load_dwordx2 v[148:149], v[204:205], off
	v_add_co_u32_e32 v204, vcc, 0xb000, v34
	s_nop 1
	v_addc_co_u32_e32 v205, vcc, 0, v35, vcc
	global_load_dwordx2 v[150:151], v[204:205], off
	v_add_co_u32_e32 v204, vcc, 0xc000, v34
	s_nop 1
	v_addc_co_u32_e32 v205, vcc, 0, v35, vcc
	global_load_dwordx2 v[152:153], v[204:205], off
	v_add_co_u32_e32 v204, vcc, 0xd000, v34
	s_nop 1
	v_addc_co_u32_e32 v205, vcc, 0, v35, vcc
	global_load_dwordx2 v[154:155], v[204:205], off
	v_add_co_u32_e32 v204, vcc, 0xe000, v34
	s_nop 1
	v_addc_co_u32_e32 v205, vcc, 0, v35, vcc
	global_load_dwordx2 v[156:157], v[204:205], off
	v_add_co_u32_e32 v204, vcc, 0xf000, v34
	s_nop 1
	v_addc_co_u32_e32 v205, vcc, 0, v35, vcc
	global_load_dwordx2 v[158:159], v[204:205], off
	v_add_co_u32_e32 v204, vcc, 0x10000, v34
	s_nop 1
	v_addc_co_u32_e32 v205, vcc, 0, v35, vcc
	global_load_dwordx2 v[160:161], v[204:205], off
	v_add_co_u32_e32 v204, vcc, 0x11000, v34
	s_nop 1
	v_addc_co_u32_e32 v205, vcc, 0, v35, vcc
	global_load_dwordx2 v[162:163], v[204:205], off
	v_add_co_u32_e32 v204, vcc, 0x12000, v34
	s_nop 1
	v_addc_co_u32_e32 v205, vcc, 0, v35, vcc
	global_load_dwordx2 v[164:165], v[204:205], off
	v_add_co_u32_e32 v204, vcc, 0x13000, v34
	s_nop 1
	v_addc_co_u32_e32 v205, vcc, 0, v35, vcc
	global_load_dwordx2 v[166:167], v[204:205], off
	v_add_co_u32_e32 v204, vcc, 0x14000, v34
	s_nop 1
	v_addc_co_u32_e32 v205, vcc, 0, v35, vcc
	global_load_dwordx2 v[168:169], v[204:205], off
	v_add_co_u32_e32 v204, vcc, 0x15000, v34
	s_nop 1
	v_addc_co_u32_e32 v205, vcc, 0, v35, vcc
	global_load_dwordx2 v[178:179], v[204:205], off
	v_add_co_u32_e32 v204, vcc, 0x16000, v34
	s_nop 1
	v_addc_co_u32_e32 v205, vcc, 0, v35, vcc
	global_load_dwordx2 v[180:181], v[204:205], off
	v_add_co_u32_e32 v204, vcc, 0x17000, v34
	s_nop 1
	v_addc_co_u32_e32 v205, vcc, 0, v35, vcc
	global_load_dwordx2 v[182:183], v[204:205], off
	v_add_co_u32_e32 v204, vcc, 0x18000, v34
	s_nop 1
	v_addc_co_u32_e32 v205, vcc, 0, v35, vcc
	global_load_dwordx2 v[184:185], v[204:205], off
	v_add_co_u32_e32 v204, vcc, 0x19000, v34
	s_nop 1
	v_addc_co_u32_e32 v205, vcc, 0, v35, vcc
	global_load_dwordx2 v[186:187], v[204:205], off
	v_add_co_u32_e32 v204, vcc, 0x1a000, v34
	s_nop 1
	v_addc_co_u32_e32 v205, vcc, 0, v35, vcc
	global_load_dwordx2 v[188:189], v[204:205], off
	v_add_co_u32_e32 v204, vcc, 0x1b000, v34
	s_nop 1
	v_addc_co_u32_e32 v205, vcc, 0, v35, vcc
	global_load_dwordx2 v[190:191], v[204:205], off
	v_add_co_u32_e32 v204, vcc, 0x1c000, v34
	s_nop 1
	v_addc_co_u32_e32 v205, vcc, 0, v35, vcc
	global_load_dwordx2 v[192:193], v[204:205], off
	v_add_co_u32_e32 v204, vcc, 0x1d000, v34
	s_nop 1
	v_addc_co_u32_e32 v205, vcc, 0, v35, vcc
	global_load_dwordx2 v[194:195], v[204:205], off
	s_nop 0
	s_mov_b32 s35, 0x16263000
	v_pk_fma_f32 v[88:89], v[68:69], v[80:81], v[88:89]
	v_pk_fma_f32 v[84:85], v[64:65], v[80:81], v[84:85]
	v_pk_fma_f32 v[88:89], v[70:71], v[58:59], v[88:89]
	v_pk_fma_f32 v[84:85], v[66:67], v[58:59], v[84:85]
	v_pk_fma_f32 v[82:83], v[60:61], v[82:83], v[78:79]
	v_pk_fma_f32 v[90:91], v[70:71], v[80:81], v[90:91]
	v_pk_fma_f32 v[86:87], v[66:67], v[80:81], v[86:87]
	v_pk_fma_f32 v[82:83], v[62:63], v[80:81], v[82:83]
	v_pk_fma_f32 v[60:61], v[60:61], v[80:81], v[78:79]
	v_pk_fma_f32 v[90:91], v[72:73], v[58:59], v[90:91]
	v_pk_fma_f32 v[86:87], v[68:69], v[58:59], v[86:87]
	v_pk_fma_f32 v[82:83], v[64:65], v[58:59], v[82:83]
	v_pk_fma_f32 v[58:59], v[62:63], v[58:59], v[60:61]
	s_waitcnt vmcnt(20) lgkmcnt(0)
	global_store_dwordx2 v[102:103], v[146:147], off
	v_pk_fma_f32 v[102:103], v[76:77], v[146:147], v[92:93]
	v_add_co_u32_e32 v92, vcc, s2, v34
	v_pk_fma_f32 v[88:89], v[72:73], v[146:147], v[88:89]
	s_nop 0
	v_addc_co_u32_e32 v93, vcc, 0, v35, vcc
	s_nop 0
	v_add_co_u32_e32 v92, vcc, s35, v2
	s_mov_b32 s35, 0x16265000
	s_nop 0
	v_addc_co_u32_e32 v93, vcc, 0, v3, vcc
	v_add_co_u32_e32 v104, vcc, s58, v34
	v_pk_fma_f32 v[84:85], v[68:69], v[146:147], v[84:85]
	s_nop 0
	v_addc_co_u32_e32 v105, vcc, 0, v35, vcc
	v_pk_fma_f32 v[96:97], v[56:57], v[146:147], v[96:97]
	v_pk_fma_f32 v[58:59], v[64:65], v[146:147], v[58:59]
	v_pk_fma_f32 v[90:91], v[74:75], v[146:147], v[90:91]
	v_pk_fma_f32 v[86:87], v[70:71], v[146:147], v[86:87]
	v_pk_fma_f32 v[82:83], v[66:67], v[146:147], v[82:83]
	s_mov_b32 s2, 0xc000
	s_waitcnt vmcnt(20) lgkmcnt(0)
	global_store_dwordx2 v[92:93], v[148:149], off offset:-4096
	s_nop 0
	v_pk_fma_f32 v[88:89], v[74:75], v[148:149], v[88:89]
	v_pk_fma_f32 v[84:85], v[70:71], v[148:149], v[84:85]
	v_pk_fma_f32 v[96:97], v[36:37], v[148:149], v[96:97]
	v_pk_fma_f32 v[58:59], v[66:67], v[148:149], v[58:59]
	v_pk_fma_f32 v[82:83], v[68:69], v[148:149], v[82:83]
	v_pk_fma_f32 v[86:87], v[72:73], v[148:149], v[86:87]
	v_pk_fma_f32 v[90:91], v[76:77], v[148:149], v[90:91]
	s_waitcnt vmcnt(20) lgkmcnt(0)
	global_store_dwordx2 v[92:93], v[150:151], off
	v_pk_fma_f32 v[92:93], v[76:77], v[150:151], v[88:89]
	v_add_co_u32_e32 v88, vcc, s8, v34
	v_pk_fma_f32 v[84:85], v[72:73], v[150:151], v[84:85]
	s_nop 0
	v_addc_co_u32_e32 v89, vcc, 0, v35, vcc
	s_nop 0
	v_add_co_u32_e32 v88, vcc, s35, v2
	v_pk_fma_f32 v[96:97], v[38:39], v[150:151], v[96:97]
	s_nop 0
	v_addc_co_u32_e32 v89, vcc, 0, v3, vcc
	v_add_co_u32_e32 v104, vcc, s59, v34
	s_mov_b32 s35, 0x16267000
	s_nop 0
	v_addc_co_u32_e32 v105, vcc, 0, v35, vcc
	v_pk_fma_f32 v[58:59], v[68:69], v[150:151], v[58:59]
	v_pk_fma_f32 v[82:83], v[70:71], v[150:151], v[82:83]
	v_pk_fma_f32 v[86:87], v[74:75], v[150:151], v[86:87]
	s_mov_b32 s8, 0x14000
	s_waitcnt vmcnt(20) lgkmcnt(0)
	global_store_dwordx2 v[88:89], v[152:153], off offset:-4096
	s_nop 0
	v_pk_fma_f32 v[84:85], v[74:75], v[152:153], v[84:85]
	v_pk_fma_f32 v[96:97], v[40:41], v[152:153], v[96:97]
	v_pk_fma_f32 v[58:59], v[70:71], v[152:153], v[58:59]
	v_pk_fma_f32 v[82:83], v[72:73], v[152:153], v[82:83]
	v_pk_fma_f32 v[86:87], v[76:77], v[152:153], v[86:87]
	s_waitcnt vmcnt(20) lgkmcnt(0)
	global_store_dwordx2 v[88:89], v[154:155], off
	v_pk_fma_f32 v[88:89], v[76:77], v[154:155], v[84:85]
	v_add_co_u32_e32 v84, vcc, s51, v34
	v_pk_fma_f32 v[96:97], v[42:43], v[154:155], v[96:97]
	s_nop 0
	v_addc_co_u32_e32 v85, vcc, 0, v35, vcc
	s_nop 0
	v_add_co_u32_e32 v84, vcc, s35, v2
	v_pk_fma_f32 v[58:59], v[72:73], v[154:155], v[58:59]
	s_nop 0
	v_addc_co_u32_e32 v85, vcc, 0, v3, vcc
	s_mov_b32 s35, 0x16269000
	v_pk_fma_f32 v[82:83], v[74:75], v[154:155], v[82:83]
	s_waitcnt vmcnt(20) lgkmcnt(0)
	v_pk_fma_f32 v[110:111], v[44:45], v[156:157], v[96:97]
	v_add_co_u32_e32 v96, vcc, s60, v34
	global_store_dwordx2 v[84:85], v[156:157], off offset:-4096
	s_nop 0
	v_addc_co_u32_e32 v97, vcc, 0, v35, vcc
	s_nop 0
	v_pk_fma_f32 v[58:59], v[74:75], v[156:157], v[58:59]
	v_pk_fma_f32 v[82:83], v[76:77], v[156:157], v[82:83]
	s_waitcnt vmcnt(20) lgkmcnt(0)
	global_store_dwordx2 v[84:85], v[158:159], off
	v_pk_fma_f32 v[84:85], v[76:77], v[158:159], v[58:59]
	v_add_co_u32_e32 v58, vcc, s27, v34
	v_pk_fma_f32 v[110:111], v[46:47], v[158:159], v[110:111]
	s_nop 0
	v_addc_co_u32_e32 v59, vcc, 0, v35, vcc
	s_nop 0
	v_add_co_u32_e32 v58, vcc, s35, v2
	s_mov_b32 s35, 0x1626b000
	s_nop 0
	v_addc_co_u32_e32 v59, vcc, 0, v3, vcc
	v_add_co_u32_e32 v62, vcc, s61, v34
	s_mov_b32 s27, 0x16000
	s_nop 0
	v_addc_co_u32_e32 v63, vcc, 0, v35, vcc
	s_waitcnt vmcnt(20) lgkmcnt(0)
	global_store_dwordx2 v[58:59], v[160:161], off offset:-4096
	v_pk_fma_f32 v[60:61], v[48:49], v[160:161], v[110:111]
	s_nop 0
	s_waitcnt vmcnt(20) lgkmcnt(0)
	global_store_dwordx2 v[58:59], v[162:163], off
	v_pk_fma_f32 v[58:59], v[50:51], v[162:163], v[60:61]
	v_add_co_u32_e32 v60, vcc, s46, v34
	s_nop 1
	v_addc_co_u32_e32 v61, vcc, 0, v35, vcc
	s_nop 0
	v_add_co_u32_e32 v60, vcc, s35, v2
	s_mov_b32 s35, 0x1626d000
	s_nop 0
	v_addc_co_u32_e32 v61, vcc, 0, v3, vcc
	v_add_co_u32_e32 v62, vcc, s82, v34
	s_waitcnt vmcnt(20) lgkmcnt(0)
	global_store_dwordx2 v[60:61], v[164:165], off offset:-4096
	v_addc_co_u32_e32 v63, vcc, 0, v35, vcc
	s_nop 0
	v_pk_fma_f32 v[62:63], v[56:57], v[148:149], v[102:103]
	v_pk_fma_f32 v[58:59], v[52:53], v[164:165], v[58:59]
	v_pk_fma_f32 v[62:63], v[36:37], v[150:151], v[62:63]
	s_waitcnt vmcnt(20) lgkmcnt(0)
	global_store_dwordx2 v[60:61], v[166:167], off
	v_add_co_u32_e32 v60, vcc, s47, v34
	v_pk_fma_f32 v[62:63], v[38:39], v[152:153], v[62:63]
	s_nop 0
	v_addc_co_u32_e32 v61, vcc, 0, v35, vcc
	s_nop 0
	v_pk_fma_f32 v[62:63], v[40:41], v[154:155], v[62:63]
	v_add_co_u32_e32 v60, vcc, s35, v2
	v_pk_fma_f32 v[62:63], v[42:43], v[156:157], v[62:63]
	s_nop 0
	v_addc_co_u32_e32 v61, vcc, 0, v3, vcc
	v_pk_fma_f32 v[62:63], v[44:45], v[158:159], v[62:63]
	s_mov_b32 s35, 0x1626f000
	v_pk_fma_f32 v[62:63], v[46:47], v[160:161], v[62:63]
	v_pk_fma_f32 v[58:59], v[54:55], v[166:167], v[58:59]
	v_pk_fma_f32 v[62:63], v[48:49], v[162:163], v[62:63]
	s_waitcnt vmcnt(20) lgkmcnt(0)
	global_store_dwordx2 v[60:61], v[168:169], off offset:-4096
	v_pk_fma_f32 v[62:63], v[50:51], v[164:165], v[62:63]
	v_pk_fma_f32 v[58:59], v[30:31], v[168:169], v[58:59]
	v_pk_fma_f32 v[62:63], v[52:53], v[166:167], v[62:63]
	s_nop 0
	v_pk_fma_f32 v[76:77], v[54:55], v[168:169], v[62:63]
	v_add_co_u32_e32 v62, vcc, s83, v34
	s_nop 1
	v_addc_co_u32_e32 v63, vcc, 0, v35, vcc
	s_nop 0
	v_pk_fma_f32 v[62:63], v[56:57], v[152:153], v[92:93]
	s_waitcnt vmcnt(20) lgkmcnt(0)
	global_store_dwordx2 v[60:61], v[178:179], off
	v_pk_fma_f32 v[60:61], v[56:57], v[150:151], v[90:91]
	v_pk_fma_f32 v[58:59], v[4:5], v[178:179], v[58:59]
	v_pk_fma_f32 v[60:61], v[36:37], v[152:153], v[60:61]
	v_pk_fma_f32 v[62:63], v[36:37], v[154:155], v[62:63]
	v_pk_fma_f32 v[60:61], v[38:39], v[154:155], v[60:61]
	v_pk_fma_f32 v[62:63], v[38:39], v[156:157], v[62:63]
	v_pk_fma_f32 v[60:61], v[40:41], v[156:157], v[60:61]
	v_pk_fma_f32 v[62:63], v[40:41], v[158:159], v[62:63]
	v_pk_fma_f32 v[60:61], v[42:43], v[158:159], v[60:61]
	v_pk_fma_f32 v[62:63], v[42:43], v[160:161], v[62:63]
	v_pk_fma_f32 v[60:61], v[44:45], v[160:161], v[60:61]
	v_pk_fma_f32 v[62:63], v[44:45], v[162:163], v[62:63]
	v_pk_fma_f32 v[60:61], v[46:47], v[162:163], v[60:61]
	v_pk_fma_f32 v[62:63], v[46:47], v[164:165], v[62:63]
	v_pk_fma_f32 v[60:61], v[48:49], v[164:165], v[60:61]
	v_pk_fma_f32 v[62:63], v[48:49], v[166:167], v[62:63]
	v_pk_fma_f32 v[60:61], v[50:51], v[166:167], v[60:61]
	v_pk_fma_f32 v[62:63], v[50:51], v[168:169], v[62:63]
	v_pk_fma_f32 v[60:61], v[52:53], v[168:169], v[60:61]
	v_pk_fma_f32 v[62:63], v[52:53], v[178:179], v[62:63]
	v_pk_fma_f32 v[68:69], v[54:55], v[178:179], v[60:61]
	v_add_co_u32_e32 v60, vcc, s3, v34
	s_nop 1
	v_addc_co_u32_e32 v61, vcc, 0, v35, vcc
	s_nop 0
	v_add_co_u32_e32 v60, vcc, s35, v2
	s_mov_b32 s35, 0x16271000
	s_nop 0
	v_addc_co_u32_e32 v61, vcc, 0, v3, vcc
	v_add_co_u32_e32 v64, vcc, s90, v34
	s_waitcnt vmcnt(20) lgkmcnt(0)
	global_store_dwordx2 v[60:61], v[180:181], off offset:-4096
	v_addc_co_u32_e32 v65, vcc, 0, v35, vcc
	s_nop 0
	v_add_co_u32_e32 v64, vcc, s48, v34
	v_pk_fma_f32 v[58:59], v[6:7], v[180:181], v[58:59]
	s_nop 0
	v_addc_co_u32_e32 v65, vcc, 0, v35, vcc
	v_add_co_u32_e32 v66, vcc, s35, v2
	s_mov_b32 s35, 0x16273000
	s_nop 0
	v_addc_co_u32_e32 v67, vcc, 0, v3, vcc
	v_add_co_u32_e32 v70, vcc, s52, v34
	v_pk_fma_f32 v[62:63], v[54:55], v[180:181], v[62:63]
	s_nop 0
	v_addc_co_u32_e32 v71, vcc, 0, v35, vcc
	s_waitcnt vmcnt(20) lgkmcnt(0)
	global_store_dwordx2 v[60:61], v[182:183], off
	s_nop 0
	v_pk_fma_f32 v[60:61], v[8:9], v[182:183], v[58:59]
	v_pk_fma_f32 v[58:59], v[56:57], v[154:155], v[86:87]
	s_waitcnt vmcnt(20) lgkmcnt(0)
	global_store_dwordx2 v[66:67], v[184:185], off offset:-4096
	s_nop 0
	v_pk_fma_f32 v[72:73], v[10:11], v[184:185], v[60:61]
	v_pk_fma_f32 v[60:61], v[56:57], v[156:157], v[88:89]
	v_pk_fma_f32 v[58:59], v[36:37], v[156:157], v[58:59]
	v_pk_fma_f32 v[60:61], v[36:37], v[158:159], v[60:61]
	v_pk_fma_f32 v[58:59], v[38:39], v[158:159], v[58:59]
	v_pk_fma_f32 v[60:61], v[38:39], v[160:161], v[60:61]
	v_pk_fma_f32 v[58:59], v[40:41], v[160:161], v[58:59]
	v_pk_fma_f32 v[60:61], v[40:41], v[162:163], v[60:61]
	v_pk_fma_f32 v[58:59], v[42:43], v[162:163], v[58:59]
	v_pk_fma_f32 v[60:61], v[42:43], v[164:165], v[60:61]
	v_pk_fma_f32 v[58:59], v[44:45], v[164:165], v[58:59]
	v_pk_fma_f32 v[60:61], v[44:45], v[166:167], v[60:61]
	v_pk_fma_f32 v[58:59], v[46:47], v[166:167], v[58:59]
	v_pk_fma_f32 v[60:61], v[46:47], v[168:169], v[60:61]
	v_pk_fma_f32 v[58:59], v[48:49], v[168:169], v[58:59]
	v_pk_fma_f32 v[60:61], v[48:49], v[178:179], v[60:61]
	v_pk_fma_f32 v[58:59], v[50:51], v[178:179], v[58:59]
	v_pk_fma_f32 v[60:61], v[50:51], v[180:181], v[60:61]
	v_pk_fma_f32 v[58:59], v[52:53], v[180:181], v[58:59]
	v_pk_fma_f32 v[60:61], v[52:53], v[182:183], v[60:61]
	v_pk_fma_f32 v[58:59], v[54:55], v[182:183], v[58:59]
	v_pk_fma_f32 v[60:61], v[54:55], v[184:185], v[60:61]
	v_pk_fma_f32 v[58:59], v[30:31], v[184:185], v[58:59]
	s_waitcnt vmcnt(20) lgkmcnt(0)
	v_pk_fma_f32 v[86:87], v[12:13], v[186:187], v[72:73]
	v_add_co_u32_e32 v72, vcc, s49, v34
	global_store_dwordx2 v[66:67], v[186:187], off
	s_nop 0
	v_addc_co_u32_e32 v73, vcc, 0, v35, vcc
	s_nop 0
	v_pk_fma_f32 v[66:67], v[56:57], v[158:159], v[82:83]
	v_add_co_u32_e32 v82, vcc, s35, v2
	v_pk_fma_f32 v[56:57], v[56:57], v[160:161], v[84:85]
	v_pk_fma_f32 v[66:67], v[36:37], v[160:161], v[66:67]
	v_addc_co_u32_e32 v83, vcc, 0, v3, vcc
	v_pk_fma_f32 v[36:37], v[36:37], v[162:163], v[56:57]
	v_pk_fma_f32 v[66:67], v[38:39], v[162:163], v[66:67]
	v_pk_fma_f32 v[36:37], v[38:39], v[164:165], v[36:37]
	v_add_co_u32_e32 v38, vcc, s88, v34
	v_pk_fma_f32 v[66:67], v[40:41], v[164:165], v[66:67]
	s_nop 0
	v_addc_co_u32_e32 v39, vcc, 0, v35, vcc
	v_pk_fma_f32 v[36:37], v[40:41], v[166:167], v[36:37]
	v_add_co_u32_e32 v40, vcc, s50, v34
	v_pk_fma_f32 v[66:67], v[42:43], v[166:167], v[66:67]
	s_nop 0
	v_addc_co_u32_e32 v41, vcc, 0, v35, vcc
	v_pk_fma_f32 v[36:37], v[42:43], v[168:169], v[36:37]
	s_mov_b32 s35, 0x16275000
	v_pk_fma_f32 v[66:67], v[44:45], v[168:169], v[66:67]
	v_pk_fma_f32 v[36:37], v[44:45], v[178:179], v[36:37]
	v_add_co_u32_e32 v44, vcc, s35, v2
	v_pk_fma_f32 v[66:67], v[46:47], v[178:179], v[66:67]
	s_nop 0
	v_addc_co_u32_e32 v45, vcc, 0, v3, vcc
	v_add_co_u32_e32 v34, vcc, s89, v34
	v_pk_fma_f32 v[36:37], v[46:47], v[180:181], v[36:37]
	s_nop 0
	v_addc_co_u32_e32 v35, vcc, 0, v35, vcc
	v_pk_fma_f32 v[66:67], v[48:49], v[180:181], v[66:67]
	v_pk_fma_f32 v[36:37], v[48:49], v[182:183], v[36:37]
	v_pk_fma_f32 v[66:67], v[50:51], v[182:183], v[66:67]
	v_pk_fma_f32 v[36:37], v[50:51], v[184:185], v[36:37]
	v_pk_fma_f32 v[66:67], v[52:53], v[184:185], v[66:67]
	v_pk_fma_f32 v[36:37], v[52:53], v[186:187], v[36:37]
	v_pk_fma_f32 v[66:67], v[54:55], v[186:187], v[66:67]
	v_pk_fma_f32 v[58:59], v[4:5], v[186:187], v[58:59]
	v_pk_fma_f32 v[60:61], v[30:31], v[186:187], v[60:61]
	s_waitcnt vmcnt(20) lgkmcnt(0)
	global_store_dwordx2 v[82:83], v[188:189], off offset:-4096
	s_nop 0
	v_pk_fma_f32 v[86:87], v[14:15], v[188:189], v[86:87]
	v_pk_fma_f32 v[36:37], v[54:55], v[188:189], v[36:37]
	v_pk_fma_f32 v[58:59], v[6:7], v[188:189], v[58:59]
	v_pk_fma_f32 v[60:61], v[4:5], v[188:189], v[60:61]
	v_pk_fma_f32 v[66:67], v[30:31], v[188:189], v[66:67]
	s_waitcnt vmcnt(20) lgkmcnt(0)
	global_store_dwordx2 v[82:83], v[190:191], off
	s_nop 0
	v_pk_fma_f32 v[42:43], v[16:17], v[190:191], v[86:87]
	v_pk_fma_f32 v[66:67], v[4:5], v[190:191], v[66:67]
	v_pk_fma_f32 v[60:61], v[6:7], v[190:191], v[60:61]
	v_pk_fma_f32 v[58:59], v[8:9], v[190:191], v[58:59]
	s_waitcnt vmcnt(20) lgkmcnt(0)
	global_store_dwordx2 v[44:45], v[192:193], off offset:-4096
	s_nop 0
	v_pk_fma_f32 v[42:43], v[24:25], v[192:193], v[42:43]
	v_pk_fma_f32 v[66:67], v[6:7], v[192:193], v[66:67]
	v_pk_fma_f32 v[60:61], v[8:9], v[192:193], v[60:61]
	v_pk_fma_f32 v[58:59], v[10:11], v[192:193], v[58:59]
	s_waitcnt vmcnt(20) lgkmcnt(0)
	global_store_dwordx2 v[44:45], v[194:195], off
	v_pk_fma_f32 v[44:45], v[26:27], v[194:195], v[42:43]
	v_add_co_u32_e32 v42, vcc, s14, v32
	s_mov_b32 s14, 0xe003000
	s_nop 0
	v_addc_co_u32_e32 v43, vcc, 0, v33, vcc
	v_add_co_u32_e32 v204, vcc, 0xe002000, v32
	s_nop 1
	v_addc_co_u32_e32 v205, vcc, 0, v33, vcc
	global_load_dword v127, v[204:205], off offset:2048
	v_add_co_u32_e32 v204, vcc, 0xe003000, v32
	s_nop 1
	v_addc_co_u32_e32 v205, vcc, 0, v33, vcc
	global_load_dword v128, v[204:205], off
	v_add_co_u32_e32 v204, vcc, 0xe009000, v32
	s_nop 1
	v_addc_co_u32_e32 v205, vcc, 0, v33, vcc
	global_load_dword v129, v[204:205], off offset:2048
	v_add_co_u32_e32 v204, vcc, 0xe00a000, v32
	s_nop 1
	v_addc_co_u32_e32 v205, vcc, 0, v33, vcc
	global_load_dword v130, v[204:205], off
	v_add_co_u32_e32 v204, vcc, 0xe010000, v32
	s_nop 1
	v_addc_co_u32_e32 v205, vcc, 0, v33, vcc
	global_load_dword v131, v[204:205], off offset:2048
	v_add_co_u32_e32 v204, vcc, 0xe011000, v32
	s_nop 1
	v_addc_co_u32_e32 v205, vcc, 0, v33, vcc
	global_load_dword v132, v[204:205], off
	v_add_co_u32_e32 v204, vcc, 0xe017000, v32
	s_nop 1
	v_addc_co_u32_e32 v205, vcc, 0, v33, vcc
	global_load_dword v133, v[204:205], off offset:2048
	v_add_co_u32_e32 v204, vcc, 0xe018000, v32
	s_nop 1
	v_addc_co_u32_e32 v205, vcc, 0, v33, vcc
	global_load_dword v134, v[204:205], off
	v_add_co_u32_e32 v204, vcc, 0xe01e000, v32
	s_nop 1
	v_addc_co_u32_e32 v205, vcc, 0, v33, vcc
	global_load_dword v135, v[204:205], off offset:2048
	v_add_co_u32_e32 v204, vcc, 0xe01f000, v32
	s_nop 1
	v_addc_co_u32_e32 v205, vcc, 0, v33, vcc
	global_load_dword v136, v[204:205], off
	v_add_co_u32_e32 v204, vcc, 0xe025000, v32
	s_nop 1
	v_addc_co_u32_e32 v205, vcc, 0, v33, vcc
	global_load_dword v196, v[204:205], off offset:2048
	v_add_co_u32_e32 v204, vcc, 0xe026000, v32
	s_nop 1
	v_addc_co_u32_e32 v205, vcc, 0, v33, vcc
	global_load_dword v197, v[204:205], off
	v_add_co_u32_e32 v204, vcc, 0xe02c000, v32
	s_nop 1
	v_addc_co_u32_e32 v205, vcc, 0, v33, vcc
	global_load_dword v198, v[204:205], off offset:2048
	v_add_co_u32_e32 v204, vcc, 0xe02d000, v32
	s_nop 1
	v_addc_co_u32_e32 v205, vcc, 0, v33, vcc
	global_load_dword v199, v[204:205], off
	v_add_co_u32_e32 v204, vcc, 0xe033000, v32
	s_nop 1
	v_addc_co_u32_e32 v205, vcc, 0, v33, vcc
	global_load_dword v206, v[204:205], off offset:2048
	v_add_co_u32_e32 v204, vcc, 0xe034000, v32
	s_nop 1
	v_addc_co_u32_e32 v205, vcc, 0, v33, vcc
	global_load_dword v207, v[204:205], off
	v_add_co_u32_e32 v42, vcc, s14, v32
	s_mov_b32 s14, 0x16277000
	s_nop 0
	v_addc_co_u32_e32 v43, vcc, 0, v33, vcc
	s_nop 0
	v_pk_fma_f32 v[66:67], v[8:9], v[194:195], v[66:67]
	v_pk_fma_f32 v[60:61], v[10:11], v[194:195], v[60:61]
	v_pk_fma_f32 v[58:59], v[12:13], v[194:195], v[58:59]
	s_waitcnt vmcnt(0)
	v_lshlrev_b32_e32 v42, 16, v127
	v_and_b32_e32 v43, 0xffff0000, v127
	s_nop 0
	v_lshlrev_b32_e32 v46, 16, v128
	v_and_b32_e32 v47, 0xffff0000, v128
	v_add_co_u32_e32 v48, vcc, s14, v2
	s_mov_b32 s14, 0xe009000
	s_nop 0
	v_addc_co_u32_e32 v49, vcc, 0, v3, vcc
	v_pk_mul_f32 v[42:43], v[42:43], v[46:47]
	v_add_co_u32_e32 v46, vcc, s14, v32
	global_store_dwordx2 v[48:49], v[42:43], off offset:-4096
	s_nop 0
	v_addc_co_u32_e32 v47, vcc, 0, v33, vcc
	s_mov_b32 s14, 0xe00a000
	s_nop 0
	v_add_co_u32_e32 v46, vcc, s14, v32
	s_mov_b32 s14, 0xe010000
	s_nop 0
	v_addc_co_u32_e32 v47, vcc, 0, v33, vcc
	s_nop 0
	v_pk_fma_f32 v[66:67], v[10:11], v[42:43], v[66:67]
	v_pk_fma_f32 v[60:61], v[12:13], v[42:43], v[60:61]
	v_pk_fma_f32 v[58:59], v[14:15], v[42:43], v[58:59]
	v_pk_fma_f32 v[44:45], v[28:29], v[42:43], v[44:45]
	s_nop 0
	v_lshlrev_b32_e32 v46, 16, v129
	v_and_b32_e32 v47, 0xffff0000, v129
	s_nop 0
	v_lshlrev_b32_e32 v50, 16, v130
	v_and_b32_e32 v51, 0xffff0000, v130
	v_pk_mul_f32 v[46:47], v[46:47], v[50:51]
	v_add_co_u32_e32 v50, vcc, s14, v32
	global_store_dwordx2 v[48:49], v[46:47], off
	s_nop 0
	v_addc_co_u32_e32 v51, vcc, 0, v33, vcc
	s_mov_b32 s14, 0xe011000
	s_nop 0
	v_add_co_u32_e32 v50, vcc, s14, v32
	s_mov_b32 s14, 0x16279000
	s_nop 0
	v_addc_co_u32_e32 v51, vcc, 0, v33, vcc
	s_nop 0
	v_add_co_u32_e32 v56, vcc, s14, v2
	s_mov_b32 s14, 0xe017000
	s_nop 0
	v_addc_co_u32_e32 v57, vcc, 0, v3, vcc
	v_pk_fma_f32 v[48:49], v[30:31], v[178:179], v[76:77]
	v_pk_fma_f32 v[66:67], v[12:13], v[46:47], v[66:67]
	v_pk_fma_f32 v[48:49], v[4:5], v[180:181], v[48:49]
	v_pk_fma_f32 v[60:61], v[14:15], v[46:47], v[60:61]
	v_pk_fma_f32 v[48:49], v[6:7], v[182:183], v[48:49]
	v_pk_fma_f32 v[58:59], v[16:17], v[46:47], v[58:59]
	v_pk_fma_f32 v[48:49], v[8:9], v[184:185], v[48:49]
	s_nop 0
	v_lshlrev_b32_e32 v50, 16, v131
	v_and_b32_e32 v51, 0xffff0000, v131
	v_pk_fma_f32 v[48:49], v[10:11], v[186:187], v[48:49]
	s_nop 0
	v_lshlrev_b32_e32 v52, 16, v132
	v_and_b32_e32 v53, 0xffff0000, v132
	v_pk_mul_f32 v[50:51], v[50:51], v[52:53]
	v_add_co_u32_e32 v54, vcc, s14, v32
	global_store_dwordx2 v[56:57], v[50:51], off offset:-4096
	s_nop 0
	v_addc_co_u32_e32 v55, vcc, 0, v33, vcc
	s_mov_b32 s14, 0xe018000
	v_pk_fma_f32 v[52:53], v[30:31], v[180:181], v[68:69]
	s_nop 0
	v_add_co_u32_e32 v54, vcc, s14, v32
	s_mov_b32 s14, 0xe01e000
	s_nop 0
	v_addc_co_u32_e32 v55, vcc, 0, v33, vcc
	s_nop 0
	v_pk_fma_f32 v[52:53], v[4:5], v[182:183], v[52:53]
	v_pk_fma_f32 v[48:49], v[12:13], v[188:189], v[48:49]
	v_pk_fma_f32 v[52:53], v[6:7], v[184:185], v[52:53]
	v_pk_fma_f32 v[48:49], v[14:15], v[190:191], v[48:49]
	v_pk_fma_f32 v[52:53], v[8:9], v[186:187], v[52:53]
	v_pk_fma_f32 v[48:49], v[16:17], v[192:193], v[48:49]
	v_pk_fma_f32 v[52:53], v[10:11], v[188:189], v[52:53]
	v_pk_fma_f32 v[66:67], v[14:15], v[50:51], v[66:67]
	v_pk_fma_f32 v[52:53], v[12:13], v[190:191], v[52:53]
	v_pk_fma_f32 v[48:49], v[24:25], v[194:195], v[48:49]
	v_pk_fma_f32 v[52:53], v[14:15], v[192:193], v[52:53]
	v_pk_fma_f32 v[60:61], v[16:17], v[50:51], v[60:61]
	v_pk_fma_f32 v[52:53], v[16:17], v[194:195], v[52:53]
	v_pk_fma_f32 v[48:49], v[26:27], v[42:43], v[48:49]
	v_pk_fma_f32 v[52:53], v[24:25], v[42:43], v[52:53]
	v_pk_fma_f32 v[58:59], v[24:25], v[50:51], v[58:59]
	v_pk_fma_f32 v[48:49], v[28:29], v[46:47], v[48:49]
	v_pk_fma_f32 v[52:53], v[26:27], v[46:47], v[52:53]
	s_nop 0
	v_lshlrev_b32_e32 v54, 16, v133
	v_and_b32_e32 v55, 0xffff0000, v133
	v_pk_fma_f32 v[52:53], v[28:29], v[50:51], v[52:53]
	s_nop 0
	v_lshlrev_b32_e32 v68, 16, v134
	v_and_b32_e32 v69, 0xffff0000, v134
	v_pk_mul_f32 v[54:55], v[54:55], v[68:69]
	global_store_dwordx2 v[56:57], v[54:55], off
	v_pk_fma_f32 v[56:57], v[30:31], v[182:183], v[62:63]
	v_add_co_u32_e32 v62, vcc, s14, v32
	s_mov_b32 s14, 0xe01f000
	s_nop 0
	v_addc_co_u32_e32 v63, vcc, 0, v33, vcc
	s_nop 0
	v_add_co_u32_e32 v62, vcc, s14, v32
	s_mov_b32 s14, 0x1627b000
	s_nop 0
	v_addc_co_u32_e32 v63, vcc, 0, v33, vcc
	s_nop 0
	v_pk_fma_f32 v[56:57], v[4:5], v[184:185], v[56:57]
	v_pk_fma_f32 v[66:67], v[16:17], v[54:55], v[66:67]
	v_pk_fma_f32 v[56:57], v[6:7], v[186:187], v[56:57]
	v_pk_fma_f32 v[60:61], v[24:25], v[54:55], v[60:61]
	v_pk_fma_f32 v[56:57], v[8:9], v[188:189], v[56:57]
	v_pk_fma_f32 v[58:59], v[26:27], v[54:55], v[58:59]
	v_pk_fma_f32 v[56:57], v[10:11], v[190:191], v[56:57]
	s_nop 0
	v_lshlrev_b32_e32 v62, 16, v135
	v_and_b32_e32 v63, 0xffff0000, v135
	v_pk_fma_f32 v[56:57], v[12:13], v[192:193], v[56:57]
	s_nop 0
	v_lshlrev_b32_e32 v68, 16, v136
	v_and_b32_e32 v69, 0xffff0000, v136
	v_pk_mul_f32 v[62:63], v[62:63], v[68:69]
	v_add_co_u32_e32 v68, vcc, s14, v2
	s_mov_b32 s14, 0xe025000
	s_nop 0
	v_addc_co_u32_e32 v69, vcc, 0, v3, vcc
	v_add_co_u32_e32 v64, vcc, s14, v32
	global_store_dwordx2 v[68:69], v[62:63], off offset:-4096
	s_nop 0
	v_addc_co_u32_e32 v65, vcc, 0, v33, vcc
	s_mov_b32 s14, 0xe026000
	s_nop 0
	v_add_co_u32_e32 v64, vcc, s14, v32
	s_mov_b32 s14, 0xe02c000
	s_nop 0
	v_addc_co_u32_e32 v65, vcc, 0, v33, vcc
	s_nop 0
	v_pk_fma_f32 v[56:57], v[14:15], v[194:195], v[56:57]
	v_pk_fma_f32 v[66:67], v[24:25], v[62:63], v[66:67]
	v_pk_fma_f32 v[56:57], v[16:17], v[42:43], v[56:57]
	v_pk_fma_f32 v[60:61], v[26:27], v[62:63], v[60:61]
	v_pk_fma_f32 v[56:57], v[24:25], v[46:47], v[56:57]
	v_pk_fma_f32 v[58:59], v[28:29], v[62:63], v[58:59]
	v_pk_fma_f32 v[56:57], v[26:27], v[50:51], v[56:57]
	s_nop 0
	v_lshlrev_b32_e32 v64, 16, v196
	v_and_b32_e32 v65, 0xffff0000, v196
	v_pk_fma_f32 v[56:57], v[28:29], v[54:55], v[56:57]
	s_nop 0
	v_lshlrev_b32_e32 v74, 16, v197
	v_and_b32_e32 v75, 0xffff0000, v197
	v_pk_mul_f32 v[64:65], v[64:65], v[74:75]
	global_store_dwordx2 v[68:69], v[64:65], off
	v_add_co_u32_e32 v68, vcc, s14, v32
	s_mov_b32 s14, 0xe02d000
	s_nop 0
	v_addc_co_u32_e32 v69, vcc, 0, v33, vcc
	s_nop 0
	v_add_co_u32_e32 v68, vcc, s14, v32
	s_mov_b32 s14, 0x1627d000
	s_nop 0
	v_addc_co_u32_e32 v69, vcc, 0, v33, vcc
	s_nop 0
	v_add_co_u32_e32 v2, vcc, s14, v2
	s_mov_b32 s14, 0xe033000
	s_nop 0
	v_addc_co_u32_e32 v3, vcc, 0, v3, vcc
	v_pk_fma_f32 v[66:67], v[26:27], v[64:65], v[66:67]
	v_pk_fma_f32 v[60:61], v[28:29], v[64:65], v[60:61]
	s_nop 0
	v_lshlrev_b32_e32 v68, 16, v198
	v_and_b32_e32 v69, 0xffff0000, v198
	s_nop 0
	v_lshlrev_b32_e32 v70, 16, v199
	v_and_b32_e32 v71, 0xffff0000, v199
	v_pk_mul_f32 v[68:69], v[68:69], v[70:71]
	v_add_co_u32_e32 v70, vcc, s14, v32
	s_mov_b32 s14, 0xe034000
	s_nop 0
	v_addc_co_u32_e32 v71, vcc, 0, v33, vcc
	v_add_co_u32_e32 v32, vcc, s14, v32
	global_store_dwordx2 v[2:3], v[68:69], off offset:-4096
	s_nop 0
	v_addc_co_u32_e32 v33, vcc, 0, v33, vcc
	s_nop 0
	s_andn2_b64 vcc, exec, s[56:57]
	s_nop 0
	v_pk_fma_f32 v[66:67], v[28:29], v[68:69], v[66:67]
	s_nop 0
	v_lshlrev_b32_e32 v32, 16, v206
	v_and_b32_e32 v33, 0xffff0000, v206
	s_nop 0
	v_lshlrev_b32_e32 v70, 16, v207
	v_and_b32_e32 v71, 0xffff0000, v207
	v_pk_mul_f32 v[32:33], v[32:33], v[70:71]
	global_store_dwordx2 v[2:3], v[32:33], off
	v_pk_fma_f32 v[2:3], v[30:31], v[190:191], v[36:37]
	s_nop 0
	v_pk_fma_f32 v[2:3], v[4:5], v[192:193], v[2:3]
	v_lshl_add_u32 v4, v122, 3, 0
	v_pk_fma_f32 v[2:3], v[6:7], v[194:195], v[2:3]
	s_nop 0
	v_pk_fma_f32 v[2:3], v[8:9], v[42:43], v[2:3]
	s_nop 0
	v_pk_fma_f32 v[2:3], v[10:11], v[46:47], v[2:3]
	s_nop 0
	v_pk_fma_f32 v[2:3], v[12:13], v[50:51], v[2:3]
	s_nop 0
	v_pk_fma_f32 v[2:3], v[14:15], v[54:55], v[2:3]
	s_nop 0
	v_pk_fma_f32 v[2:3], v[16:17], v[62:63], v[2:3]
	s_nop 0
	v_pk_fma_f32 v[2:3], v[24:25], v[64:65], v[2:3]
	s_nop 0
	v_pk_fma_f32 v[2:3], v[26:27], v[68:69], v[2:3]
	s_nop 0
	v_pk_fma_f32 v[2:3], v[28:29], v[32:33], v[2:3]
	ds_write2st64_b64 v4, v[44:45], v[48:49] offset1:8
	ds_write2st64_b64 v4, v[52:53], v[56:57] offset0:16 offset1:24
	ds_write2st64_b64 v4, v[58:59], v[60:61] offset0:32 offset1:40
	ds_write2st64_b64 v4, v[66:67], v[2:3] offset0:48 offset1:56
	s_waitcnt lgkmcnt(0)
	s_barrier
	s_cbranch_vccnz .LBB0_638
	v_readlane_b32 s14, v243, 3
	v_and_b32_e32 v2, 64, v203
	v_add_u32_e32 v32, 64, v2
	v_add_u32_e32 v25, s14, v19
	ds_read_b128 v[14:17], v25
	ds_read_b128 v[10:13], v25 offset:16
	v_xor_b32_e32 v2, 1, v203
	v_cmp_lt_i32_e32 vcc, v2, v32
	ds_read_b128 v[6:9], v25 offset:2048
	s_waitcnt lgkmcnt(2)
	v_mov_b32_e32 v3, v16
	v_cndmask_b32_e32 v2, v203, v2, vcc
	v_lshlrev_b32_e32 v33, 2, v2
	v_mov_b32_e32 v2, v15
	v_mov_b32_e32 v4, v14
	v_mov_b32_e32 v5, v17
	v_pk_add_f32 v[2:3], v[2:3], v[4:5]
	s_waitcnt lgkmcnt(1)
	v_mov_b32_e32 v26, v11
	v_add_f32_e32 v2, v2, v3
	v_add_f32_e32 v24, 0, v2
	ds_read_b128 v[2:5], v25 offset:2064
	v_mov_b32_e32 v27, v12
	v_mov_b32_e32 v28, v10
	v_mov_b32_e32 v29, v13
	v_pk_add_f32 v[26:27], v[26:27], v[28:29]
	s_waitcnt lgkmcnt(1)
	v_add_f32_e32 v28, v6, v7
	v_pk_add_f32 v[26:27], v[26:27], v[26:27] op_sel:[0,1] op_sel_hi:[1,0]
	v_add_f32_e32 v30, v8, v9
	s_waitcnt lgkmcnt(0)
	v_mov_b32_e32 v25, v2
	v_mov_b32_e32 v27, v3
	v_mov_b32_e32 v29, v4
	v_mov_b32_e32 v31, v5
	v_pk_add_f32 v[24:25], v[24:25], v[26:27]
	v_pk_add_f32 v[26:27], v[28:29], v[30:31]
	s_add_u32 s22, s22, s0
	v_pk_add_f32 v[24:25], v[24:25], v[26:27]
	v_xor_b32_e32 v26, 2, v203
	v_add_f32_e32 v24, v24, v25
	ds_bpermute_b32 v25, v33, v24
	v_cmp_lt_i32_e32 vcc, v26, v32
	s_addc_u32 s23, s23, s1
	s_add_u32 s0, s34, s0
	v_cndmask_b32_e32 v26, v203, v26, vcc
	v_lshlrev_b32_e32 v36, 2, v26
	s_waitcnt lgkmcnt(0)
	v_add_f32_e32 v24, v24, v25
	ds_bpermute_b32 v25, v36, v24
	v_xor_b32_e32 v26, 4, v203
	v_cmp_lt_i32_e32 vcc, v26, v32
	s_addc_u32 s1, s19, s1
	v_readlane_b32 s14, v244, 27
	v_cndmask_b32_e32 v26, v203, v26, vcc
	v_lshlrev_b32_e32 v37, 2, v26
	s_waitcnt lgkmcnt(0)
	v_add_f32_e32 v24, v24, v25
	ds_bpermute_b32 v25, v37, v24
	v_xor_b32_e32 v26, 8, v203
	v_cmp_lt_i32_e32 vcc, v26, v32
	s_add_u32 s14, s28, s14
	s_addc_u32 s15, s18, 0
	v_cndmask_b32_e32 v26, v203, v26, vcc
	v_lshlrev_b32_e32 v38, 2, v26
	s_waitcnt lgkmcnt(0)
	v_add_f32_e32 v24, v24, v25
	ds_bpermute_b32 v25, v38, v24
	v_xor_b32_e32 v26, 16, v203
	v_cmp_lt_i32_e32 vcc, v26, v32
	s_mul_i32 s18, s15, 0x7000
	s_mul_hi_u32 s19, s14, 0x7000
	v_cndmask_b32_e32 v26, v203, v26, vcc
	v_lshlrev_b32_e32 v39, 2, v26
	s_waitcnt lgkmcnt(0)
	v_add_f32_e32 v24, v24, v25
	ds_bpermute_b32 v25, v39, v24
	v_xor_b32_e32 v26, 32, v203
	v_cmp_lt_i32_e32 vcc, v26, v32
	s_add_i32 s19, s19, s18
	s_mul_i32 s18, s14, 0x7000
	v_cndmask_b32_e32 v26, v203, v26, vcc
	v_lshlrev_b32_e32 v48, 2, v26
	s_waitcnt lgkmcnt(0)
	v_add_f32_e32 v24, v24, v25
	ds_bpermute_b32 v25, v48, v24
	s_add_u32 s18, s92, s18
	s_addc_u32 s19, s93, s19
	v_lshlrev_b32_e32 v172, 2, v125
	s_add_u32 s18, s18, 0x3800
	s_waitcnt lgkmcnt(0)
	v_add_f32_e32 v32, v24, v25
	v_fmamk_f32 v15, v32, 0xba800000, v15
	v_fmamk_f32 v14, v32, 0xba800000, v14
	v_fmamk_f32 v17, v32, 0xba800000, v17
	v_fmac_f32_e32 v16, 0xba800000, v32
	v_pk_mul_f32 v[24:25], v[16:17], v[16:17]
	v_pk_mul_f32 v[26:27], v[14:15], v[14:15]
	v_fmamk_f32 v11, v32, 0xba800000, v11
	v_pk_mov_b32 v[28:29], v[26:27], v[24:25] op_sel:[1,0]
	v_mov_b32_e32 v27, v25
	v_pk_add_f32 v[24:25], v[28:29], v[26:27]
	v_fmamk_f32 v10, v32, 0xba800000, v10
	v_fmamk_f32 v13, v32, 0xba800000, v13
	v_fmac_f32_e32 v12, 0xba800000, v32
	v_pk_add_f32 v[24:25], v[24:25], v[24:25] op_sel_hi:[0,1]
	v_pk_mul_f32 v[26:27], v[12:13], v[12:13]
	v_pk_mul_f32 v[28:29], v[10:11], v[10:11]
	v_fmamk_f32 v6, v32, 0xba800000, v6
	v_pk_mov_b32 v[30:31], v[28:29], v[26:27] op_sel:[1,0]
	v_mov_b32_e32 v29, v27
	v_fmamk_f32 v7, v32, 0xba800000, v7
	v_fmac_f32_e32 v8, 0xba800000, v32
	v_mul_f32_e32 v24, v6, v6
	v_pk_add_f32 v[26:27], v[30:31], v[28:29]
	v_fmamk_f32 v9, v32, 0xba800000, v9
	v_pk_fma_f32 v[28:29], v[6:7], v[6:7], v[24:25] op_sel_hi:[1,1,0]
	v_mul_f32_e32 v24, v8, v8
	v_pk_add_f32 v[26:27], v[26:27], v[26:27] op_sel_hi:[0,1]
	v_pk_fma_f32 v[30:31], v[8:9], v[8:9], v[24:25] op_sel_hi:[1,1,0]
	v_fmamk_f32 v5, v32, 0xba800000, v5
	v_fmamk_f32 v4, v32, 0xba800000, v4
	v_fmamk_f32 v3, v32, 0xba800000, v3
	v_fmac_f32_e32 v2, 0xba800000, v32
	v_mul_f32_e32 v28, v2, v2
	v_mul_f32_e32 v30, v3, v3
	v_mul_f32_e32 v24, v4, v4
	v_mul_f32_e32 v26, v5, v5
	v_pk_add_f32 v[28:29], v[28:29], v[30:31]
	v_pk_add_f32 v[30:31], v[24:25], v[26:27]
	v_lshl_add_u64 v[44:45], s[0:1], 0, v[172:173]
	v_pk_add_f32 v[28:29], v[28:29], v[30:31]
	v_lshl_add_u64 v[46:47], s[22:23], 0, v[172:173]
	v_add_f32_e32 v40, v28, v29
	ds_bpermute_b32 v41, v33, v40
	s_addc_u32 s19, s19, 0
	flat_load_dwordx4 v[28:31], v[44:45]
	flat_load_dwordx4 v[32:35], v[46:47]
	global_load_dwordx4 v[24:27], v20, s[18:19]
	s_waitcnt lgkmcnt(0)
	v_add_f32_e32 v40, v40, v41
	ds_bpermute_b32 v36, v36, v40
	s_waitcnt lgkmcnt(0)
	v_add_f32_e32 v36, v40, v36
	ds_bpermute_b32 v37, v37, v36
	s_waitcnt lgkmcnt(0)
	v_add_f32_e32 v36, v36, v37
	ds_bpermute_b32 v37, v38, v36
	s_waitcnt lgkmcnt(0)
	v_add_f32_e32 v49, v36, v37
	ds_bpermute_b32 v50, v39, v49
	flat_load_dwordx4 v[36:39], v[44:45] offset:16
	flat_load_dwordx4 v[40:43], v[46:47] offset:16
	s_waitcnt lgkmcnt(0)
	v_add_f32_e32 v49, v49, v50
	ds_bpermute_b32 v48, v48, v49
	s_waitcnt lgkmcnt(0)
	v_add_f32_e32 v48, v49, v48
	v_fmamk_f32 v48, v48, 0x3a800000, v171
	v_mul_f32_e32 v49, 0x4f800000, v48
	v_cmp_gt_f32_e32 vcc, s9, v48
	s_nop 1
	v_cndmask_b32_e32 v48, v48, v49, vcc
	v_sqrt_f32_e32 v49, v48
	s_nop 0
	v_add_u32_e32 v50, -1, v49
	v_fma_f32 v51, -v50, v49, v48
	v_cmp_ge_f32_e64 s[0:1], 0, v51
	v_add_u32_e32 v51, 1, v49
	s_nop 0
	v_cndmask_b32_e64 v50, v49, v50, s[0:1]
	v_fma_f32 v49, -v51, v49, v48
	v_cmp_lt_f32_e64 s[0:1], 0, v49
	s_nop 1
	v_cndmask_b32_e64 v49, v50, v51, s[0:1]
	v_mul_f32_e32 v50, 0x37800000, v49
	v_cndmask_b32_e32 v49, v49, v50, vcc
	v_cmp_class_f32_e32 vcc, v48, v200
	s_nop 1
	v_cndmask_b32_e32 v48, v49, v48, vcc
	v_div_scale_f32 v49, s[0:1], v48, v48, 1.0
	v_rcp_f32_e32 v50, v49
	s_lshl_b64 s[0:1], s[14:15], 11
	v_fma_f32 v51, -v49, v50, 1.0
	v_fmac_f32_e32 v50, v51, v50
	v_div_scale_f32 v51, vcc, 1.0, v48, 1.0
	v_mul_f32_e32 v52, v51, v50
	v_fma_f32 v53, -v49, v52, v51
	v_fmac_f32_e32 v52, v53, v50
	v_fma_f32 v49, -v49, v52, v51
	v_div_fmas_f32 v49, v49, v50, v52
	v_div_fixup_f32 v48, v49, v48, 1.0
	v_pk_mul_f32 v[14:15], v[14:15], v[48:49] op_sel_hi:[1,0]
	v_pk_mul_f32 v[16:17], v[16:17], v[48:49] op_sel_hi:[1,0]
	v_pk_mul_f32 v[10:11], v[10:11], v[48:49] op_sel_hi:[1,0]
	v_pk_mul_f32 v[12:13], v[12:13], v[48:49] op_sel_hi:[1,0]
	s_waitcnt vmcnt(0)
	v_pk_fma_f32 v[14:15], v[28:29], v[14:15], v[32:33]
	v_lshlrev_b32_e32 v52, 16, v26
	v_and_b32_e32 v53, 0xffff0000, v26
	v_mul_f32_e32 v26, 0xbfb8aa3b, v14
	v_exp_f32_e32 v26, v26
	v_mul_f32_e32 v28, 0xbfb8aa3b, v15
	v_exp_f32_e32 v29, v28
	v_pk_fma_f32 v[16:17], v[30:31], v[16:17], v[34:35]
	v_add_f32_e32 v26, 1.0, v26
	v_rcp_f32_e32 v28, v26
	v_add_f32_e32 v26, 1.0, v29
	v_mul_f32_e32 v29, 0xbfb8aa3b, v16
	v_exp_f32_e32 v30, v29
	v_mul_f32_e32 v29, 0xbfb8aa3b, v17
	v_exp_f32_e32 v31, v29
	v_rcp_f32_e32 v29, v26
	v_add_f32_e32 v26, 1.0, v30
	v_rcp_f32_e32 v30, v26
	v_add_f32_e32 v26, 1.0, v31
	v_rcp_f32_e32 v31, v26
	v_pk_mul_f32 v[14:15], v[14:15], v[28:29]
	v_lshlrev_b32_e32 v50, 16, v24
	v_pk_fma_f32 v[10:11], v[36:37], v[10:11], v[40:41]
	v_pk_fma_f32 v[12:13], v[38:39], v[12:13], v[42:43]
	v_pk_mul_f32 v[16:17], v[16:17], v[30:31]
	v_mul_f32_e32 v28, 0xbfb8aa3b, v10
	v_mul_f32_e32 v29, 0xbfb8aa3b, v11
	v_mul_f32_e32 v30, 0xbfb8aa3b, v12
	v_mul_f32_e32 v31, 0xbfb8aa3b, v13
	v_exp_f32_e32 v28, v28
	v_exp_f32_e32 v29, v29
	v_exp_f32_e32 v30, v30
	v_exp_f32_e32 v31, v31
	v_add_f32_e32 v28, 1.0, v28
	v_add_f32_e32 v29, 1.0, v29
	v_add_f32_e32 v30, 1.0, v30
	v_add_f32_e32 v31, 1.0, v31
	v_rcp_f32_e32 v28, v28
	v_rcp_f32_e32 v29, v29
	v_rcp_f32_e32 v30, v30
	v_rcp_f32_e32 v31, v31
	v_and_b32_e32 v51, 0xffff0000, v24
	v_lshlrev_b32_e32 v24, 16, v25
	v_and_b32_e32 v25, 0xffff0000, v25
	v_lshlrev_b32_e32 v26, 16, v27
	v_and_b32_e32 v27, 0xffff0000, v27
	v_pk_mul_f32 v[10:11], v[10:11], v[28:29]
	v_pk_mul_f32 v[12:13], v[12:13], v[30:31]
	v_pk_mul_f32 v[16:17], v[16:17], v[24:25]
	v_pk_mul_f32 v[24:25], v[12:13], v[26:27]
	v_pk_mul_f32 v[12:13], v[10:11], v[52:53]
	v_lshl_add_u64 v[36:37], v[22:23], 0, s[0:1]
	v_pk_mul_f32 v[14:15], v[14:15], v[50:51]
	v_pk_mul_f32 v[6:7], v[6:7], v[48:49] op_sel_hi:[1,0]
	v_cvt_pk_bf16_f32 v10, v14, v15
	v_cvt_pk_bf16_f32 v11, v16, v17
	v_cvt_pk_bf16_f32 v12, v12, v13
	v_cvt_pk_bf16_f32 v13, v24, v25
	global_store_dwordx4 v[36:37], v[10:13], off
	global_load_dwordx4 v[14:17], v21, s[18:19]
	s_nop 0
	flat_load_dwordx4 v[10:13], v[46:47] offset:2048
	flat_load_dwordx4 v[24:27], v[44:45] offset:2048
	flat_load_dwordx4 v[28:31], v[44:45] offset:2064
	flat_load_dwordx4 v[32:35], v[46:47] offset:2064
	v_pk_mul_f32 v[8:9], v[8:9], v[48:49] op_sel_hi:[1,0]
	v_pk_mul_f32 v[2:3], v[2:3], v[48:49] op_sel_hi:[1,0]
	v_pk_mul_f32 v[4:5], v[4:5], v[48:49] op_sel_hi:[1,0]
	s_waitcnt vmcnt(0) lgkmcnt(0)
	v_pk_fma_f32 v[6:7], v[24:25], v[6:7], v[10:11]
	v_pk_fma_f32 v[8:9], v[26:27], v[8:9], v[12:13]
	v_mul_f32_e32 v10, 0xbfb8aa3b, v6
	v_mul_f32_e32 v11, 0xbfb8aa3b, v7
	v_mul_f32_e32 v12, 0xbfb8aa3b, v8
	v_mul_f32_e32 v13, 0xbfb8aa3b, v9
	v_exp_f32_e32 v10, v10
	v_exp_f32_e32 v11, v11
	v_exp_f32_e32 v12, v12
	v_exp_f32_e32 v13, v13
	v_add_f32_e32 v10, 1.0, v10
	v_add_f32_e32 v11, 1.0, v11
	v_add_f32_e32 v12, 1.0, v12
	v_add_f32_e32 v13, 1.0, v13
	v_rcp_f32_e32 v10, v10
	v_rcp_f32_e32 v11, v11
	v_rcp_f32_e32 v12, v12
	v_rcp_f32_e32 v13, v13
	v_pk_fma_f32 v[2:3], v[28:29], v[2:3], v[32:33]
	v_pk_fma_f32 v[4:5], v[30:31], v[4:5], v[34:35]
	v_pk_mul_f32 v[6:7], v[6:7], v[10:11]
	v_pk_mul_f32 v[8:9], v[8:9], v[12:13]
	v_mul_f32_e32 v10, 0xbfb8aa3b, v2
	v_mul_f32_e32 v11, 0xbfb8aa3b, v3
	v_mul_f32_e32 v12, 0xbfb8aa3b, v4
	v_mul_f32_e32 v13, 0xbfb8aa3b, v5
	v_exp_f32_e32 v10, v10
	v_exp_f32_e32 v11, v11
	v_exp_f32_e32 v12, v12
	v_exp_f32_e32 v13, v13
	v_add_f32_e32 v10, 1.0, v10
	v_add_f32_e32 v11, 1.0, v11
	v_add_f32_e32 v12, 1.0, v12
	v_add_f32_e32 v13, 1.0, v13
	v_rcp_f32_e32 v10, v10
	v_rcp_f32_e32 v11, v11
	v_rcp_f32_e32 v12, v12
	v_rcp_f32_e32 v13, v13
	v_lshlrev_b32_e32 v40, 16, v16
	v_and_b32_e32 v41, 0xffff0000, v16
	v_lshlrev_b32_e32 v16, 16, v17
	v_and_b32_e32 v17, 0xffff0000, v17
	v_pk_mul_f32 v[2:3], v[2:3], v[10:11]
	v_pk_mul_f32 v[4:5], v[4:5], v[12:13]
	v_lshlrev_b32_e32 v38, 16, v14
	v_and_b32_e32 v39, 0xffff0000, v14
	v_lshlrev_b32_e32 v14, 16, v15
	v_and_b32_e32 v15, 0xffff0000, v15
	v_pk_mul_f32 v[10:11], v[4:5], v[16:17]
	v_pk_mul_f32 v[4:5], v[2:3], v[40:41]
	v_pk_mul_f32 v[8:9], v[8:9], v[14:15]
	v_pk_mul_f32 v[6:7], v[6:7], v[38:39]
	s_nop 0
	v_cvt_pk_bf16_f32 v2, v6, v7
	v_cvt_pk_bf16_f32 v3, v8, v9
	v_cvt_pk_bf16_f32 v4, v4, v5
	v_cvt_pk_bf16_f32 v5, v10, v11
	global_store_dwordx4 v[36:37], v[2:5], off offset:1024
	s_branch .LBB0_638
